# cache-shift copy moved into the P1 GEMM K-loop as background traffic (2 chunks per iteration); prologue/attention copies disabled
# baseline (speedup 1.0000x reference)
.LBB0_140:
	s_mov_b64 s[12:13], s[92:93]
	v_writelane_b32 v239, s9, 52
	s_mov_b32 s14, s94
	v_writelane_b32 v239, s12, 53
	s_add_u32 s6, s92, 0xdc00000
	s_addc_u32 s7, s93, 0
	v_writelane_b32 v239, s13, 54
	v_writelane_b32 v239, s14, 55
	v_writelane_b32 v239, s15, 56
	v_writelane_b32 v239, s90, 57
	s_add_u32 s8, s92, 0xee00000
	s_addc_u32 s9, s93, 0
	v_writelane_b32 v239, s91, 58
	v_writelane_b32 v239, s16, 59
	s_andn2_b64 vcc, exec, s[4:5]
	s_ashr_i32 s82, s94, 31
	v_writelane_b32 v239, s17, 60
	v_writelane_b32 v239, s20, 61
	s_nop 1
	v_writelane_b32 v239, s21, 62
	v_writelane_b32 v239, s24, 63
	s_nop 1
	v_writelane_b32 v238, s25, 0
	v_writelane_b32 v238, s54, 1
	s_nop 1
	v_writelane_b32 v238, s55, 2
	v_writelane_b32 v238, s58, 3
	s_nop 1
	v_writelane_b32 v238, s59, 4
	v_writelane_b32 v238, s74, 5
	s_nop 1
	v_writelane_b32 v238, s75, 6
	v_writelane_b32 v238, s76, 7
	s_nop 1
	v_writelane_b32 v238, s77, 8
	v_writelane_b32 v238, s84, 9
	s_nop 1
	v_writelane_b32 v238, s85, 10
	v_writelane_b32 v238, s86, 11
	s_nop 1
	v_writelane_b32 v238, s87, 12
	v_writelane_b32 v238, s88, 13
	s_nop 1
	v_writelane_b32 v238, s89, 14
	s_cbranch_vccnz .LBB0_285
	v_mbcnt_lo_u32_b32 v251, -1, 0
	v_mbcnt_hi_u32_b32 v251, -1, v251
	v_mov_b32_e32 v250, s80
	v_mov_b32_e32 v228, 0x80403
	v_lshlrev_b32_e32 v251, 4, v251
	v_min_u32_e32 v252, 0x1feff, v250
	v_add_u32_e32 v250, 0x800, v250
	v_mul_hi_u32 v253, v252, v228
	v_mul_u32_u24_e32 v254, 0x1ff0, v253
	v_and_b32_e32 v255, 7, v253
	v_sub_u32_e32 v254, v252, v254
	v_lshrrev_b32_e32 v253, 3, v253
	v_lshlrev_b32_e32 v255, 23, v255
	v_cmp_ne_u32_e32 vcc, 0, v253
	v_lshl_add_u32 v254, v254, 10, v255
	v_add_u32_e32 v254, v254, v251
	v_lshl_add_u32 v249, v253, 26, v254
	v_add_u32_e32 v254, 0x4000, v254
	v_add_u32_e32 v249, 0x605e000, v249
	s_cbranch_vccnz .Lgc_v_pre
	global_load_dwordx4 v[244:247], v254, s[48:49] nt
	s_branch .Lgc_d_pre
.Lgc_v_pre:
	global_load_dwordx4 v[244:247], v254, s[50:51] nt
.Lgc_d_pre:
	v_ashrrev_i32_e32 v1, 31, v8
	v_lshrrev_b32_e32 v1, 26, v1
	v_add_u32_e32 v1, v8, v1
	v_ashrrev_i32_e32 v9, 6, v1
	v_bfe_i32 v1, v8, 27, 1
	v_lshlrev_b32_e32 v0, 4, v8
	v_lshrrev_b32_e32 v1, 22, v1
	v_add_u32_e32 v1, v0, v1
	v_and_b32_e32 v1, 0xfffffc00, v1
	v_sub_u32_e32 v1, v0, v1
	v_lshrrev_b32_e32 v2, 4, v1
	v_bitop3_b32 v1, v2, v1, 32 bitop3:0x6c
	v_ashrrev_i32_e32 v3, 31, v1
	v_lshrrev_b32_e32 v3, 26, v3
	v_add_u32_e32 v3, v1, v3
	v_lshlrev_b32_e32 v2, 3, v9
	v_ashrrev_i32_e32 v10, 6, v3
	v_and_b32_e32 v3, 0xc0, v3
	v_and_b32_e32 v2, -16, v2
	v_sub_u32_e32 v1, v1, v3
	v_mov_b32_e32 v3, 1
	v_add_u32_e32 v2, v10, v2
	v_ashrrev_i16_sdwa v1, v3, sext(v1) dst_sel:DWORD dst_unused:UNUSED_PAD src0_sel:DWORD src1_sel:BYTE_0
	v_lshlrev_b32_e32 v4, 5, v9
	v_bfe_i32 v11, v1, 0, 16
	v_lshlrev_b32_e32 v1, 1, v2
	v_lshrrev_b32_e32 v5, 2, v2
	v_and_b32_e32 v6, 3, v10
	s_mov_b32 s4, 0xfffe0
	v_and_b32_e32 v4, 32, v4
	v_and_b32_e32 v1, 24, v1
	v_and_b32_e32 v5, 4, v5
	v_and_or_b32 v6, v2, s4, v6
	v_or3_b32 v1, v6, v5, v1
	v_add_lshl_u32 v4, v4, v11, 1
	v_add_u32_e32 v0, 0x2000, v0
	v_lshl_add_u32 v134, v1, 12, v4
	v_ashrrev_i32_e32 v1, 31, v0
	v_lshrrev_b32_e32 v1, 22, v1
	v_add_u32_e32 v1, v0, v1
	v_ashrrev_i32_e32 v12, 10, v1
	v_mul_i32_i24_e32 v1, 0x400, v12
	v_sub_u32_e32 v0, v0, v1
	v_lshrrev_b32_e32 v1, 4, v0
	v_bitop3_b32 v0, v1, v0, 32 bitop3:0x6c
	v_lshl_add_u32 v132, v2, 12, v4
	v_ashrrev_i32_e32 v2, 31, v0
	v_lshrrev_b32_e32 v2, 26, v2
	v_add_u32_e32 v2, v0, v2
	v_lshlrev_b32_e32 v1, 3, v12
	v_ashrrev_i32_e32 v13, 6, v2
	v_and_b32_e32 v2, 0xc0, v2
	v_and_b32_e32 v1, -16, v1
	v_sub_u32_e32 v0, v0, v2
	s_ashr_i32 s1, s0, 6
	v_add_u32_e32 v1, v13, v1
	v_ashrrev_i16_sdwa v0, v3, sext(v0) dst_sel:DWORD dst_unused:UNUSED_PAD src0_sel:DWORD src1_sel:BYTE_0
	v_and_b32_e32 v3, 3, v13
	s_ashr_i32 s19, s18, 31
	s_ashr_i32 s41, s40, 31
	v_and_or_b32 v3, v1, s4, v3
	s_ashr_i32 s10, s0, 8
	s_lshl_b32 s83, s1, 10
	s_lshl_b64 s[4:5], s[18:19], 20
	s_lshl_b64 s[12:13], s[40:41], 20
	s_add_u32 s74, s72, s12
	v_lshlrev_b32_e32 v4, 5, v12
	v_bfe_i32 v14, v0, 0, 16
	v_lshlrev_b32_e32 v0, 1, v1
	v_lshrrev_b32_e32 v2, 2, v1
	s_addc_u32 s75, s73, s13
	s_add_i32 s84, s83, 0
	v_and_b32_e32 v4, 32, v4
	v_and_b32_e32 v0, 24, v0
	v_and_b32_e32 v2, 4, v2
	s_add_i32 m0, s84, 0x10000
	v_or3_b32 v0, v3, v2, v0
	v_add_lshl_u32 v2, v4, v14, 1
	global_load_lds_dwordx4 v134, s[74:75]
	s_add_i32 m0, s84, 0x12000
	v_lshl_add_u32 v138, v0, 12, v2
	s_add_u32 s12, s74, 0x80000
	global_load_lds_dwordx4 v138, s[74:75]
	s_addc_u32 s13, s75, 0
	s_add_i32 m0, s84, 0x14000
	v_lshl_add_u32 v136, v1, 12, v2
	global_load_lds_dwordx4 v134, s[12:13]
	s_add_i32 m0, s84, 0x16000
	s_add_u32 s42, s56, s4
	s_addc_u32 s43, s57, s5
	s_add_i32 s85, s84, 0x2000
	global_load_lds_dwordx4 v138, s[12:13]
	s_mov_b32 m0, s84
	s_add_u32 s4, s42, 0x80000
	global_load_lds_dwordx4 v132, s[42:43]
	s_mov_b32 m0, s85
	s_addc_u32 s5, s43, 0
	s_add_i32 s86, s84, 0x4000
	global_load_lds_dwordx4 v136, s[42:43]
	s_mov_b32 m0, s86
	s_add_i32 s87, s84, 0x6000
	global_load_lds_dwordx4 v132, s[4:5]
	s_mov_b32 m0, s87
	v_mov_b32_e32 v141, 0
	global_load_lds_dwordx4 v136, s[4:5]
	v_mov_b32_e32 v135, v141
	v_mov_b32_e32 v139, v141
	v_mov_b32_e32 v133, v141
	v_mov_b32_e32 v137, v141
	s_cmp_eq_u32 s10, 1
	s_mov_b32 s26, s96
	s_mov_b32 s88, 0
	v_lshl_add_u64 v[6:7], s[74:75], 0, v[134:135]
	v_lshl_add_u64 v[4:5], s[74:75], 0, v[138:139]
	v_lshl_add_u64 v[0:1], s[42:43], 0, v[132:133]
	s_cselect_b64 s[4:5], -1, 0
	s_cmp_lg_u32 s10, 1
	v_lshl_add_u64 v[2:3], s[42:43], 0, v[136:137]
	s_cbranch_scc1 .LBB0_143
	s_barrier

.LBB0_149:
	ds_read_b128 v[128:131], v164
	ds_read_b128 v[150:153], v164 offset:1024
	ds_read_b128 v[154:157], v164 offset:2048
	ds_read_b128 v[158:161], v164 offset:3072
	ds_read_b128 v[170:173], v165
	ds_read_b128 v[174:177], v165 offset:1024
	ds_read_b128 v[178:181], v165 offset:2048
	ds_read_b128 v[182:185], v165 offset:3072
	s_add_u32 s17, s42, 0xfff80080
	s_addc_u32 s19, s43, -1
	s_cmp_eq_u32 s16, 28
	s_cselect_b32 s77, s0, s19
	s_cselect_b32 s76, s1, s17
	s_cselect_b32 s75, s12, s15
	s_cselect_b32 s74, s13, s14
	v_lshl_add_u64 v[218:219], s[42:43], 0, v[142:143]
	s_add_i32 m0, s84, 0xc000
	ds_read_b128 v[186:189], v166
	ds_read_b128 v[190:193], v166 offset:1024
	ds_read_b128 v[194:197], v166 offset:2048
	ds_read_b128 v[198:201], v166 offset:3072
	ds_read_b128 v[202:205], v166 offset:4096
	ds_read_b128 v[206:209], v166 offset:5120
	ds_read_b128 v[210:213], v166 offset:6144
	ds_read_b128 v[214:217], v166 offset:7168
	global_load_lds_dwordx4 v[218:219], off
	v_lshl_add_u64 v[218:219], s[42:43], 0, v[144:145]
	s_add_i32 m0, s84, 0xe000
	s_nop 0
	global_load_lds_dwordx4 v[218:219], off
	v_min_u32_e32 v252, 0x1feff, v250
	v_add_u32_e32 v250, 0x800, v250
	v_mul_hi_u32 v253, v252, v228
	v_mul_u32_u24_e32 v254, 0x1ff0, v253
	v_and_b32_e32 v255, 7, v253
	v_sub_u32_e32 v254, v252, v254
	v_lshrrev_b32_e32 v253, 3, v253
	v_lshlrev_b32_e32 v255, 23, v255
	v_cmp_ne_u32_e32 vcc, 0, v253
	v_lshl_add_u32 v254, v254, 10, v255
	v_add_u32_e32 v254, v254, v251
	v_lshl_add_u32 v248, v253, 26, v254
	v_add_u32_e32 v254, 0x4000, v254
	v_add_u32_e32 v248, 0x605e000, v248
	s_cbranch_vccnz .Lgc_v_a
	global_load_dwordx4 v[240:243], v254, s[48:49] nt
	s_branch .Lgc_d_a
.Lgc_v_a:
	global_load_dwordx4 v[240:243], v254, s[50:51] nt
.Lgc_d_a:
	s_waitcnt vmcnt(11)
	s_waitcnt lgkmcnt(0)
	s_barrier
	s_setprio 1
	s_waitcnt lgkmcnt(0)
	v_mfma_f32_16x16x32_bf16 v[124:127], v[128:131], v[186:189], v[124:127]
	v_mfma_f32_16x16x32_bf16 v[120:123], v[154:157], v[186:189], v[120:123]
	v_mfma_f32_16x16x32_bf16 v[108:111], v[128:131], v[194:197], v[108:111]
	v_mfma_f32_16x16x32_bf16 v[104:107], v[154:157], v[194:197], v[104:107]
	v_mfma_f32_16x16x32_bf16 v[92:95], v[128:131], v[202:205], v[92:95]
	v_mfma_f32_16x16x32_bf16 v[88:91], v[154:157], v[202:205], v[88:91]
	v_mfma_f32_16x16x32_bf16 v[76:79], v[128:131], v[210:213], v[76:79]
	v_mfma_f32_16x16x32_bf16 v[72:75], v[154:157], v[210:213], v[72:75]
	v_mfma_f32_16x16x32_bf16 v[124:127], v[150:153], v[190:193], v[124:127]
	v_mfma_f32_16x16x32_bf16 v[120:123], v[158:161], v[190:193], v[120:123]
	v_mfma_f32_16x16x32_bf16 v[108:111], v[150:153], v[198:201], v[108:111]
	v_mfma_f32_16x16x32_bf16 v[104:107], v[158:161], v[198:201], v[104:107]
	v_mfma_f32_16x16x32_bf16 v[92:95], v[150:153], v[206:209], v[92:95]
	v_mfma_f32_16x16x32_bf16 v[88:91], v[158:161], v[206:209], v[88:91]
	v_mfma_f32_16x16x32_bf16 v[76:79], v[150:153], v[214:217], v[76:79]
	v_mfma_f32_16x16x32_bf16 v[72:75], v[158:161], v[214:217], v[72:75]
	s_setprio 0
	s_setprio 1
	v_mfma_f32_16x16x32_bf16 v[116:119], v[170:173], v[186:189], v[116:119]
	v_mfma_f32_16x16x32_bf16 v[112:115], v[178:181], v[186:189], v[112:115]
	v_mfma_f32_16x16x32_bf16 v[100:103], v[170:173], v[194:197], v[100:103]
	v_mfma_f32_16x16x32_bf16 v[96:99], v[178:181], v[194:197], v[96:99]
	v_mfma_f32_16x16x32_bf16 v[84:87], v[170:173], v[202:205], v[84:87]
	v_mfma_f32_16x16x32_bf16 v[80:83], v[178:181], v[202:205], v[80:83]
	v_mfma_f32_16x16x32_bf16 v[68:71], v[170:173], v[210:213], v[68:71]
	v_mfma_f32_16x16x32_bf16 v[64:67], v[178:181], v[210:213], v[64:67]
	v_mfma_f32_16x16x32_bf16 v[116:119], v[174:177], v[190:193], v[116:119]
	v_mfma_f32_16x16x32_bf16 v[112:115], v[182:185], v[190:193], v[112:115]
	v_mfma_f32_16x16x32_bf16 v[100:103], v[174:177], v[198:201], v[100:103]
	v_mfma_f32_16x16x32_bf16 v[96:99], v[182:185], v[198:201], v[96:99]
	v_mfma_f32_16x16x32_bf16 v[84:87], v[174:177], v[206:209], v[84:87]
	v_mfma_f32_16x16x32_bf16 v[80:83], v[182:185], v[206:209], v[80:83]
	v_mfma_f32_16x16x32_bf16 v[68:71], v[174:177], v[214:217], v[68:71]
	v_mfma_f32_16x16x32_bf16 v[64:67], v[182:185], v[214:217], v[64:67]
	s_setprio 0
	s_barrier
	s_add_i32 s17, s93, s83
	v_lshl_add_u64 v[218:219], s[74:75], 0, v[134:135]
	s_mov_b32 m0, s17
	ds_read_b128 v[186:189], v166 offset:16384
	ds_read_b128 v[190:193], v166 offset:17408
	ds_read_b128 v[194:197], v166 offset:18432
	ds_read_b128 v[198:201], v166 offset:19456
	ds_read_b128 v[202:205], v166 offset:20480
	ds_read_b128 v[206:209], v166 offset:21504
	ds_read_b128 v[210:213], v166 offset:22528
	ds_read_b128 v[214:217], v166 offset:23552
	global_load_lds_dwordx4 v[218:219], off
	s_add_i32 m0, s17, 0x2000
	s_add_u32 s20, s74, 0x80000
	v_lshl_add_u64 v[220:221], s[74:75], 0, v[138:139]
	s_addc_u32 s21, s75, 0
	s_add_i32 s17, s94, s83
	global_load_lds_dwordx4 v[220:221], off
	v_lshl_add_u64 v[222:223], s[20:21], 0, v[134:135]
	s_mov_b32 m0, s17
	v_lshl_add_u64 v[224:225], s[76:77], 0, v[136:137]
	global_load_lds_dwordx4 v[222:223], off
	v_lshl_add_u64 v[222:223], s[20:21], 0, v[138:139]
	s_add_i32 m0, s17, 0x2000
	s_nop 0
	global_load_lds_dwordx4 v[222:223], off
	v_lshl_add_u64 v[222:223], s[76:77], 0, v[132:133]
	s_mov_b32 m0, s84
	s_nop 0
	global_load_lds_dwordx4 v[222:223], off
	s_mov_b32 m0, s85
	s_nop 0
	global_load_lds_dwordx4 v[224:225], off
	s_waitcnt vmcnt(10)
	global_store_dwordx4 v249, v[244:247], s[66:67] nt
	s_waitcnt lgkmcnt(0)
	s_barrier
	s_setprio 1
	s_waitcnt lgkmcnt(0)
	v_mfma_f32_16x16x32_bf16 v[60:63], v[128:131], v[186:189], v[60:63]
	v_mfma_f32_16x16x32_bf16 v[56:59], v[154:157], v[186:189], v[56:59]
	v_mfma_f32_16x16x32_bf16 v[44:47], v[128:131], v[194:197], v[44:47]
	v_mfma_f32_16x16x32_bf16 v[40:43], v[154:157], v[194:197], v[40:43]
	v_mfma_f32_16x16x32_bf16 v[28:31], v[128:131], v[202:205], v[28:31]
	v_mfma_f32_16x16x32_bf16 v[24:27], v[154:157], v[202:205], v[24:27]
	v_mfma_f32_16x16x32_bf16 v[12:15], v[128:131], v[210:213], v[12:15]
	v_mfma_f32_16x16x32_bf16 v[8:11], v[154:157], v[210:213], v[8:11]
	v_mfma_f32_16x16x32_bf16 v[60:63], v[150:153], v[190:193], v[60:63]
	v_mfma_f32_16x16x32_bf16 v[56:59], v[158:161], v[190:193], v[56:59]
	v_mfma_f32_16x16x32_bf16 v[44:47], v[150:153], v[198:201], v[44:47]
	v_mfma_f32_16x16x32_bf16 v[40:43], v[158:161], v[198:201], v[40:43]
	v_mfma_f32_16x16x32_bf16 v[28:31], v[150:153], v[206:209], v[28:31]
	v_mfma_f32_16x16x32_bf16 v[24:27], v[158:161], v[206:209], v[24:27]
	v_mfma_f32_16x16x32_bf16 v[12:15], v[150:153], v[214:217], v[12:15]
	v_mfma_f32_16x16x32_bf16 v[8:11], v[158:161], v[214:217], v[8:11]
	s_setprio 0
	s_setprio 1
	v_mfma_f32_16x16x32_bf16 v[52:55], v[170:173], v[186:189], v[52:55]
	v_mfma_f32_16x16x32_bf16 v[48:51], v[178:181], v[186:189], v[48:51]
	v_mfma_f32_16x16x32_bf16 v[36:39], v[170:173], v[194:197], v[36:39]
	v_mfma_f32_16x16x32_bf16 v[32:35], v[178:181], v[194:197], v[32:35]
	v_mfma_f32_16x16x32_bf16 v[20:23], v[170:173], v[202:205], v[20:23]
	v_mfma_f32_16x16x32_bf16 v[16:19], v[178:181], v[202:205], v[16:19]
	v_mfma_f32_16x16x32_bf16 v[4:7], v[170:173], v[210:213], v[4:7]
	v_mfma_f32_16x16x32_bf16 v[0:3], v[178:181], v[210:213], v[0:3]
	v_mfma_f32_16x16x32_bf16 v[52:55], v[174:177], v[190:193], v[52:55]
	v_mfma_f32_16x16x32_bf16 v[48:51], v[182:185], v[190:193], v[48:51]
	v_mfma_f32_16x16x32_bf16 v[36:39], v[174:177], v[198:201], v[36:39]
	v_mfma_f32_16x16x32_bf16 v[32:35], v[182:185], v[198:201], v[32:35]
	v_mfma_f32_16x16x32_bf16 v[20:23], v[174:177], v[206:209], v[20:23]
	v_mfma_f32_16x16x32_bf16 v[16:19], v[182:185], v[206:209], v[16:19]
	v_mfma_f32_16x16x32_bf16 v[4:7], v[174:177], v[214:217], v[4:7]
	v_mfma_f32_16x16x32_bf16 v[0:3], v[182:185], v[214:217], v[0:3]
	s_setprio 0
	s_barrier
	s_add_i32 s17, 0, 0x18000
	v_add_u32_e32 v140, s17, v162
	s_add_i32 s19, 0, 0x1c000
	ds_read_b128 v[128:131], v140
	ds_read_b128 v[150:153], v140 offset:1024
	ds_read_b128 v[154:157], v140 offset:2048
	ds_read_b128 v[158:161], v140 offset:3072
	v_add_u32_e32 v140, s19, v162
	ds_read_b128 v[170:173], v140
	ds_read_b128 v[174:177], v140 offset:1024
	ds_read_b128 v[178:181], v140 offset:2048
	ds_read_b128 v[182:185], v140 offset:3072
	s_add_u32 s20, s76, 0x80000
	s_addc_u32 s21, s77, 0
	s_mov_b32 m0, s86
	v_lshl_add_u64 v[226:227], s[20:21], 0, v[132:133]
	ds_read_b128 v[186:189], v166 offset:32768
	ds_read_b128 v[190:193], v166 offset:33792
	ds_read_b128 v[194:197], v166 offset:34816
	ds_read_b128 v[198:201], v166 offset:35840
	ds_read_b128 v[202:205], v166 offset:36864
	ds_read_b128 v[206:209], v166 offset:37888
	ds_read_b128 v[210:213], v166 offset:38912
	ds_read_b128 v[214:217], v166 offset:39936
	global_load_lds_dwordx4 v[226:227], off
	v_lshl_add_u64 v[226:227], s[20:21], 0, v[136:137]
	s_mov_b32 m0, s87
	s_nop 0
	global_load_lds_dwordx4 v[226:227], off
	v_min_u32_e32 v252, 0x1feff, v250
	v_add_u32_e32 v250, 0x800, v250
	v_mul_hi_u32 v253, v252, v228
	v_mul_u32_u24_e32 v254, 0x1ff0, v253
	v_and_b32_e32 v255, 7, v253
	v_sub_u32_e32 v254, v252, v254
	v_lshrrev_b32_e32 v253, 3, v253
	v_lshlrev_b32_e32 v255, 23, v255
	v_cmp_ne_u32_e32 vcc, 0, v253
	v_lshl_add_u32 v254, v254, 10, v255
	v_add_u32_e32 v254, v254, v251
	v_lshl_add_u32 v249, v253, 26, v254
	v_add_u32_e32 v254, 0x4000, v254
	v_add_u32_e32 v249, 0x605e000, v249
	s_cbranch_vccnz .Lgc_v_b
	global_load_dwordx4 v[244:247], v254, s[48:49] nt
	s_branch .Lgc_d_b

.Lgc_d_b:
	s_waitcnt vmcnt(11)
	s_waitcnt lgkmcnt(0)
	s_barrier
	s_setprio 1
	s_waitcnt lgkmcnt(0)
	v_mfma_f32_16x16x32_bf16 v[124:127], v[128:131], v[186:189], v[124:127]
	v_mfma_f32_16x16x32_bf16 v[120:123], v[154:157], v[186:189], v[120:123]
	v_mfma_f32_16x16x32_bf16 v[108:111], v[128:131], v[194:197], v[108:111]
	v_mfma_f32_16x16x32_bf16 v[104:107], v[154:157], v[194:197], v[104:107]
	v_mfma_f32_16x16x32_bf16 v[92:95], v[128:131], v[202:205], v[92:95]
	v_mfma_f32_16x16x32_bf16 v[88:91], v[154:157], v[202:205], v[88:91]
	v_mfma_f32_16x16x32_bf16 v[76:79], v[128:131], v[210:213], v[76:79]
	v_mfma_f32_16x16x32_bf16 v[72:75], v[154:157], v[210:213], v[72:75]
	v_mfma_f32_16x16x32_bf16 v[124:127], v[150:153], v[190:193], v[124:127]
	v_mfma_f32_16x16x32_bf16 v[120:123], v[158:161], v[190:193], v[120:123]
	v_mfma_f32_16x16x32_bf16 v[108:111], v[150:153], v[198:201], v[108:111]
	v_mfma_f32_16x16x32_bf16 v[104:107], v[158:161], v[198:201], v[104:107]
	v_mfma_f32_16x16x32_bf16 v[92:95], v[150:153], v[206:209], v[92:95]
	v_mfma_f32_16x16x32_bf16 v[88:91], v[158:161], v[206:209], v[88:91]
	v_mfma_f32_16x16x32_bf16 v[76:79], v[150:153], v[214:217], v[76:79]
	v_mfma_f32_16x16x32_bf16 v[72:75], v[158:161], v[214:217], v[72:75]
	s_setprio 0
	s_setprio 1
	v_mfma_f32_16x16x32_bf16 v[116:119], v[170:173], v[186:189], v[116:119]
	v_mfma_f32_16x16x32_bf16 v[112:115], v[178:181], v[186:189], v[112:115]
	v_mfma_f32_16x16x32_bf16 v[100:103], v[170:173], v[194:197], v[100:103]
	v_mfma_f32_16x16x32_bf16 v[96:99], v[178:181], v[194:197], v[96:99]
	v_mfma_f32_16x16x32_bf16 v[84:87], v[170:173], v[202:205], v[84:87]
	v_mfma_f32_16x16x32_bf16 v[80:83], v[178:181], v[202:205], v[80:83]
	v_mfma_f32_16x16x32_bf16 v[68:71], v[170:173], v[210:213], v[68:71]
	v_mfma_f32_16x16x32_bf16 v[64:67], v[178:181], v[210:213], v[64:67]
	v_mfma_f32_16x16x32_bf16 v[116:119], v[174:177], v[190:193], v[116:119]
	v_mfma_f32_16x16x32_bf16 v[112:115], v[182:185], v[190:193], v[112:115]
	v_mfma_f32_16x16x32_bf16 v[100:103], v[174:177], v[198:201], v[100:103]
	v_mfma_f32_16x16x32_bf16 v[96:99], v[182:185], v[198:201], v[96:99]
	v_mfma_f32_16x16x32_bf16 v[84:87], v[174:177], v[206:209], v[84:87]
	v_mfma_f32_16x16x32_bf16 v[80:83], v[182:185], v[206:209], v[80:83]
	v_mfma_f32_16x16x32_bf16 v[68:71], v[174:177], v[214:217], v[68:71]
	v_mfma_f32_16x16x32_bf16 v[64:67], v[182:185], v[214:217], v[64:67]
	s_setprio 0
	s_barrier
	s_add_i32 s17, s17, s83
	v_lshl_add_u64 v[218:219], v[218:219], 0, s[10:11]
	s_mov_b32 m0, s17
	ds_read_b128 v[186:189], v166 offset:49152
	ds_read_b128 v[190:193], v166 offset:50176
	ds_read_b128 v[194:197], v166 offset:51200
	ds_read_b128 v[198:201], v166 offset:52224
	ds_read_b128 v[202:205], v166 offset:53248
	ds_read_b128 v[206:209], v166 offset:54272
	ds_read_b128 v[210:213], v166 offset:55296
	ds_read_b128 v[214:217], v166 offset:56320
	global_load_lds_dwordx4 v[218:219], off
	s_add_i32 m0, s17, 0x2000
	s_add_u32 s20, s74, 0x80080
	v_lshl_add_u64 v[218:219], v[220:221], 0, s[10:11]
	s_addc_u32 s21, s75, 0
	s_add_i32 s17, s19, s83
	global_load_lds_dwordx4 v[218:219], off
	v_lshl_add_u64 v[218:219], s[20:21], 0, v[134:135]
	s_mov_b32 m0, s17
	s_nop 0
	global_load_lds_dwordx4 v[218:219], off
	v_lshl_add_u64 v[218:219], s[20:21], 0, v[138:139]
	s_add_i32 m0, s17, 0x2000
	s_nop 0
	global_load_lds_dwordx4 v[218:219], off
	v_lshl_add_u64 v[218:219], v[222:223], 0, s[10:11]
	s_mov_b32 m0, s91
	s_nop 0
	global_load_lds_dwordx4 v[218:219], off
	v_lshl_add_u64 v[218:219], v[224:225], 0, s[10:11]
	s_mov_b32 m0, s92
	s_nop 0
	global_load_lds_dwordx4 v[218:219], off
	s_waitcnt vmcnt(10)
	global_store_dwordx4 v248, v[240:243], s[66:67] nt
	s_waitcnt lgkmcnt(0)
	s_barrier
	s_setprio 1
	s_waitcnt lgkmcnt(0)
	v_mfma_f32_16x16x32_bf16 v[60:63], v[128:131], v[186:189], v[60:63]
	v_mfma_f32_16x16x32_bf16 v[56:59], v[154:157], v[186:189], v[56:59]
	v_mfma_f32_16x16x32_bf16 v[44:47], v[128:131], v[194:197], v[44:47]
	v_mfma_f32_16x16x32_bf16 v[40:43], v[154:157], v[194:197], v[40:43]
	v_mfma_f32_16x16x32_bf16 v[28:31], v[128:131], v[202:205], v[28:31]
	v_mfma_f32_16x16x32_bf16 v[24:27], v[154:157], v[202:205], v[24:27]
	v_mfma_f32_16x16x32_bf16 v[12:15], v[128:131], v[210:213], v[12:15]
	v_mfma_f32_16x16x32_bf16 v[8:11], v[154:157], v[210:213], v[8:11]
	v_mfma_f32_16x16x32_bf16 v[60:63], v[150:153], v[190:193], v[60:63]
	v_mfma_f32_16x16x32_bf16 v[56:59], v[158:161], v[190:193], v[56:59]
	v_mfma_f32_16x16x32_bf16 v[44:47], v[150:153], v[198:201], v[44:47]
	v_mfma_f32_16x16x32_bf16 v[40:43], v[158:161], v[198:201], v[40:43]
	v_mfma_f32_16x16x32_bf16 v[28:31], v[150:153], v[206:209], v[28:31]
	v_mfma_f32_16x16x32_bf16 v[24:27], v[158:161], v[206:209], v[24:27]
	v_mfma_f32_16x16x32_bf16 v[12:15], v[150:153], v[214:217], v[12:15]
	v_mfma_f32_16x16x32_bf16 v[8:11], v[158:161], v[214:217], v[8:11]
	s_setprio 0
	s_setprio 1
	v_mfma_f32_16x16x32_bf16 v[52:55], v[170:173], v[186:189], v[52:55]
	v_mfma_f32_16x16x32_bf16 v[48:51], v[178:181], v[186:189], v[48:51]
	v_mfma_f32_16x16x32_bf16 v[36:39], v[170:173], v[194:197], v[36:39]
	v_mfma_f32_16x16x32_bf16 v[32:35], v[178:181], v[194:197], v[32:35]
	v_mfma_f32_16x16x32_bf16 v[20:23], v[170:173], v[202:205], v[20:23]
	v_mfma_f32_16x16x32_bf16 v[16:19], v[178:181], v[202:205], v[16:19]
	v_mfma_f32_16x16x32_bf16 v[4:7], v[170:173], v[210:213], v[4:7]
	v_mfma_f32_16x16x32_bf16 v[0:3], v[178:181], v[210:213], v[0:3]
	v_mfma_f32_16x16x32_bf16 v[52:55], v[174:177], v[190:193], v[52:55]
	v_mfma_f32_16x16x32_bf16 v[48:51], v[182:185], v[190:193], v[48:51]
	v_mfma_f32_16x16x32_bf16 v[36:39], v[174:177], v[198:201], v[36:39]
	v_mfma_f32_16x16x32_bf16 v[32:35], v[182:185], v[198:201], v[32:35]
	v_mfma_f32_16x16x32_bf16 v[20:23], v[174:177], v[206:209], v[20:23]
	v_mfma_f32_16x16x32_bf16 v[16:19], v[182:185], v[206:209], v[16:19]
	v_mfma_f32_16x16x32_bf16 v[4:7], v[174:177], v[214:217], v[4:7]
	v_mfma_f32_16x16x32_bf16 v[0:3], v[182:185], v[214:217], v[0:3]
	s_setprio 0
	s_barrier
	s_add_i32 s16, s16, 2
	s_add_u32 s42, s42, 0x100
	s_addc_u32 s43, s43, 0
	s_add_u32 s14, s14, 0x100
	s_addc_u32 s15, s15, 0
	s_cmp_gt_u32 s16, 29
	s_cbranch_scc0 .LBB0_149
	s_and_b64 vcc, exec, s[30:31]
	s_cbranch_vccz .LBB0_152
	s_barrier

.LBB0_284:
	s_waitcnt vmcnt(0)
	global_store_dwordx4 v249, v[244:247], s[66:67] nt
	v_readlane_b32 s92, v239, 53
	v_readlane_b32 s90, v239, 57
	v_readlane_b32 s16, v239, 59
	v_readlane_b32 s20, v239, 61
	v_readlane_b32 s24, v239, 63
	v_readlane_b32 s54, v238, 1
	v_readlane_b32 s58, v238, 3
	v_readlane_b32 s74, v238, 5
	v_readlane_b32 s76, v238, 7
	v_readlane_b32 s84, v238, 9
	v_readlane_b32 s86, v238, 11
	v_readlane_b32 s88, v238, 13
	v_readlane_b32 s93, v239, 54
	v_readlane_b32 s94, v239, 55
	v_readlane_b32 s91, v239, 58
	v_readlane_b32 s17, v239, 60
	v_readlane_b32 s21, v239, 62
	v_readlane_b32 s25, v238, 0
	v_readlane_b32 s55, v238, 2
	v_readlane_b32 s59, v238, 4
	v_readlane_b32 s75, v238, 6
	v_readlane_b32 s77, v238, 8
	v_readlane_b32 s85, v238, 10
	v_readlane_b32 s87, v238, 12
	v_readlane_b32 s89, v238, 14
	s_mov_b32 s96, s26
	s_barrier
	v_readlane_b32 s95, v239, 56

.LBB0_344:
	s_or_b32 s14, s0, s73
	s_or_b32 s0, s0, s87
	s_mov_b32 s0, 0
	s_lshl_b32 s12, s0, 9
	s_cmpk_gt_i32 s0, 0x1fef
	s_cselect_b64 s[18:19], -1, 0
	s_add_i32 s13, s12, 0xffc02000
	s_and_b64 s[0:1], s[18:19], exec
	s_cselect_b32 s15, s13, s12
	s_mul_hi_i32 s0, s15, 0x80402011
	s_add_i32 s0, s0, s15
	s_lshr_b32 s1, s0, 31
	s_ashr_i32 s0, s0, 18
	s_add_i32 s16, s0, s1
	s_add_i32 s17, s16, 1
	s_and_b64 s[12:13], s[18:19], exec
	v_mbcnt_lo_u32_b32 v172, -1, 0
	v_mbcnt_hi_u32_b32 v172, -1, v172
	s_cselect_b32 s12, s51, s49
	s_cselect_b32 s13, s50, s48
	s_and_b32 s1, s14, s88
	s_lshr_b32 s14, s14, s87
	v_ashrrev_i32_e32 v36, 3, v172
	s_or_b32 s1, s1, s84
	s_lshl_b32 s14, s14, s89
	v_subrev_u32_e32 v37, 64, v36
	s_add_i32 s1, s1, s14
	v_lshlrev_b32_e32 v37, s87, v37
	v_lshlrev_b32_e32 v1, 4, v172
	v_add_u32_e32 v37, s1, v37
	v_and_b32_e32 v41, 0x70, v1
	v_max_i32_e32 v37, 0, v37
	v_lshl_or_b32 v163, v37, 7, v41
	v_subrev_u32_e32 v37, 56, v36
	v_lshlrev_b32_e32 v37, s87, v37
	v_add_u32_e32 v37, s1, v37
	v_max_i32_e32 v37, 0, v37
	v_lshl_or_b32 v165, v37, 7, v41
	v_subrev_u32_e32 v37, 48, v36
	v_lshlrev_b32_e32 v37, s87, v37
	v_add_u32_e32 v37, s1, v37
	v_max_i32_e32 v37, 0, v37
	v_lshl_or_b32 v167, v37, 7, v41
	v_subrev_u32_e32 v37, 40, v36
	v_lshlrev_b32_e32 v37, s87, v37
	v_add_u32_e32 v37, s1, v37
	v_max_i32_e32 v37, 0, v37
	v_lshl_or_b32 v186, v37, 7, v41
	v_subrev_u32_e32 v37, 32, v36
	v_lshlrev_b32_e32 v37, s87, v37
	v_add_u32_e32 v37, s1, v37
	v_max_i32_e32 v37, 0, v37
	v_lshl_or_b32 v144, v37, 7, v41
	v_subrev_u32_e32 v37, 24, v36
	v_lshlrev_b32_e32 v37, s87, v37
	v_add_u32_e32 v37, s1, v37
	v_max_i32_e32 v37, 0, v37
	v_lshl_or_b32 v154, v37, 7, v41
	v_add_lshl_u32 v37, v36, -16, s87
	v_add_u32_e32 v37, s1, v37
	v_max_i32_e32 v37, 0, v37
	v_lshl_or_b32 v156, v37, 7, v41
	v_add_lshl_u32 v37, v36, -8, s87
	v_add_u32_e32 v37, s1, v37
	v_max_i32_e32 v37, 0, v37
	v_lshl_or_b32 v158, v37, 7, v41
	v_lshlrev_b32_e32 v37, s87, v36
	v_add_u32_e32 v37, s1, v37
	v_max_i32_e32 v37, 0, v37
	v_lshl_or_b32 v160, v37, 7, v41
	v_add_lshl_u32 v37, v36, 8, s87
	v_add_u32_e32 v37, s1, v37
	v_max_i32_e32 v37, 0, v37
	v_lshl_or_b32 v162, v37, 7, v41
	v_add_lshl_u32 v37, v36, 16, s87
	v_add_u32_e32 v37, s1, v37
	v_and_b32_e32 v176, 31, v172
	v_max_i32_e32 v37, 0, v37
	v_lshlrev_b32_e32 v0, s87, v176
	v_lshl_or_b32 v164, v37, 7, v41
	v_add_lshl_u32 v37, v36, 24, s87
	s_mul_i32 s0, s17, 0x7fc00
	v_add_u32_e32 v174, s1, v0
	v_add_u32_e32 v37, s1, v37
	v_add_u32_e32 v187, s15, v172
	v_ashrrev_i32_e32 v173, 5, v172
	v_add_u32_e32 v0, s34, v174
	v_max_i32_e32 v37, 0, v37
	v_mov_b32_e32 v188, s17
	v_mov_b32_e32 v189, s16
	v_cmp_gt_i32_e32 vcc, s0, v187
	v_mul_lo_u32 v0, v0, s75
	v_lshlrev_b32_e32 v40, 4, v173
	v_lshl_or_b32 v166, v37, 7, v41
	v_cndmask_b32_e32 v37, v188, v189, vcc
	v_lshlrev_b32_e32 v38, 4, v187
	v_add3_u32 v0, v40, s10, v0
	v_lshl_add_u32 v190, v37, 14, v38
	v_add_u32_e32 v37, 64, v187
	v_add_u32_e32 v0, 0xffffff80, v36
	v_add_u32_e32 v8, 0xffffff90, v36
	v_add_u32_e32 v20, 0xffffffa0, v36
	v_add_u32_e32 v28, 0xffffffb0, v36
	v_cmp_gt_i32_e32 vcc, s0, v37
	v_lshlrev_b32_e32 v0, s87, v0
	v_lshlrev_b32_e32 v8, s87, v8
	v_lshlrev_b32_e32 v20, s87, v20
	v_lshlrev_b32_e32 v28, s87, v28
	v_cndmask_b32_e32 v38, v188, v189, vcc
	v_lshlrev_b32_e32 v37, 4, v37
	v_add_u32_e32 v0, s1, v0
	v_add_u32_e32 v8, s1, v8
	v_add_u32_e32 v20, s1, v20
	v_add_u32_e32 v28, s1, v28
	v_lshl_add_u32 v191, v38, 14, v37
	v_add_u32_e32 v37, 0x80, v187
	v_max_i32_e32 v0, 0, v0
	v_max_i32_e32 v8, 0, v8
	v_max_i32_e32 v20, 0, v20
	v_max_i32_e32 v28, 0, v28
	v_cmp_gt_i32_e32 vcc, s0, v37
	v_lshl_or_b32 v124, v0, 7, v41
	v_add_u32_e32 v0, 0xffffff88, v36
	v_lshl_or_b32 v126, v8, 7, v41
	v_add_u32_e32 v8, 0xffffff98, v36
	v_lshl_or_b32 v155, v20, 7, v41
	v_add_u32_e32 v20, 0xffffffa8, v36
	v_lshl_or_b32 v159, v28, 7, v41
	v_add_u32_e32 v28, 0xffffffb8, v36
	v_cndmask_b32_e32 v38, v188, v189, vcc
	v_lshlrev_b32_e32 v37, 4, v37
	v_lshlrev_b32_e32 v0, s87, v0
	v_lshlrev_b32_e32 v8, s87, v8
	v_lshlrev_b32_e32 v20, s87, v20
	v_lshlrev_b32_e32 v28, s87, v28
	v_lshl_add_u32 v192, v38, 14, v37
	v_add_u32_e32 v37, 0xc0, v187
	s_add_u32 s36, s13, 0x4000
	v_add_u32_e32 v0, s1, v0
	v_add_u32_e32 v8, s1, v8
	v_add_u32_e32 v20, s1, v20
	v_add_u32_e32 v28, s1, v28
	v_cmp_gt_i32_e32 vcc, s0, v37
	s_addc_u32 s37, s12, 0
	v_max_i32_e32 v0, 0, v0
	v_max_i32_e32 v8, 0, v8
	v_max_i32_e32 v20, 0, v20
	v_max_i32_e32 v28, 0, v28
	v_cndmask_b32_e32 v38, v188, v189, vcc
	v_lshlrev_b32_e32 v37, 4, v37
	v_lshl_or_b32 v125, v0, 7, v41
	global_load_dwordx4 v[0:3], v124, s[40:41]
	global_load_dwordx4 v[4:7], v125, s[40:41]
	v_lshl_or_b32 v127, v8, 7, v41
	global_load_dwordx4 v[8:11], v126, s[40:41]
	global_load_dwordx4 v[12:15], v127, s[40:41]
	v_lshl_or_b32 v157, v20, 7, v41
	global_load_dwordx4 v[20:23], v155, s[40:41]
	global_load_dwordx4 v[24:27], v157, s[40:41]
	v_lshl_or_b32 v161, v28, 7, v41
	global_load_dwordx4 v[28:31], v159, s[40:41]
	global_load_dwordx4 v[32:35], v161, s[40:41]
	global_load_dwordx4 v[48:51], v163, s[40:41]
	global_load_dwordx4 v[52:55], v165, s[40:41]
	global_load_dwordx4 v[56:59], v167, s[40:41]
	global_load_dwordx4 v[60:63], v186, s[40:41]
	global_load_dwordx4 v[92:95], v154, s[40:41]
	global_load_dwordx4 v[96:99], v156, s[40:41]
	global_load_dwordx4 v[100:103], v158, s[40:41]
	global_load_dwordx4 v[104:107], v160, s[40:41]
	global_load_dwordx4 v[108:111], v162, s[40:41]
	global_load_dwordx4 v[112:115], v164, s[40:41]
	global_load_dwordx4 v[116:119], v144, s[40:41]
	global_load_dwordx4 v[120:123], v166, s[40:41]
	global_load_dwordx4 v[146:149], v190, s[36:37] nt
	global_load_dwordx4 v[150:153], v191, s[36:37] nt
	v_lshl_add_u32 v193, v38, 14, v37
	global_load_dwordx4 v[178:181], v192, s[36:37] nt
	global_load_dwordx4 v[182:185], v193, s[36:37] nt
	s_and_b64 s[12:13], s[18:19], exec
	s_mov_b32 s12, 0xa05e000
	s_cselect_b32 s12, s12, 0x605e000
	s_add_u32 s18, s66, s12
	v_lshlrev_b32_e32 v177, 2, v173
	s_addc_u32 s19, s67, 0
	v_mul_lo_u32 v43, v36, s76
	v_add_u32_e32 v168, s72, v41
	v_add_u32_e32 v44, 0x480, v43
	v_add_u32_e32 v45, 0x900, v43
	v_add_u32_e32 v46, 0xd80, v43
	v_mul_u32_u24_e32 v42, 0x90, v176
	v_add_u32_e32 v175, v168, v43
	v_add_u32_e32 v128, v168, v44
	v_add_u32_e32 v129, v168, v45
	v_add_u32_e32 v130, v168, v46
	s_waitcnt vmcnt(23)
	ds_write_b128 v175, v[0:3]
	s_waitcnt vmcnt(22)
	ds_write_b128 v128, v[4:7]
	s_waitcnt vmcnt(21)
	ds_write_b128 v129, v[8:11]
	s_waitcnt vmcnt(20)
	ds_write_b128 v130, v[12:15]
	v_add3_u32 v131, s72, v42, v40
	ds_read_b128 v[0:3], v131
	ds_read_b128 v[36:39], v131 offset:32
	s_waitcnt lgkmcnt(1)
	v_mfma_f32_32x32x16_bf16 v[0:15], v[0:3], v[240:243], 0
	v_add_u32_e32 v47, s74, v41
	v_add_u32_e32 v132, v47, v43
	v_add3_u32 v133, s74, v42, v40
	ds_read_b128 v[40:43], v131 offset:96
	v_add_u32_e32 v134, v47, v44
	v_add_u32_e32 v135, v47, v45
	v_add_u32_e32 v136, v47, v46
	s_waitcnt lgkmcnt(1)
	v_mfma_f32_32x32x16_bf16 v[0:15], v[36:39], v[244:247], v[0:15]
	ds_read_b128 v[36:39], v131 offset:64
	s_waitcnt vmcnt(19)
	ds_write_b128 v132, v[20:23]
	s_waitcnt vmcnt(18)
	ds_write_b128 v134, v[24:27]
	s_waitcnt vmcnt(17)
	ds_write_b128 v135, v[28:31]
	s_waitcnt vmcnt(16)
	ds_write_b128 v136, v[32:35]
	ds_read_b128 v[20:23], v133
	s_waitcnt lgkmcnt(5)
	v_mfma_f32_32x32x16_bf16 v[0:15], v[36:39], v[248:251], v[0:15]
	v_mfma_f32_32x32x16_bf16 v[0:15], v[40:43], v[252:255], v[0:15]
	s_waitcnt lgkmcnt(0)
	v_mfma_f32_32x32x16_bf16 v[32:47], v[20:23], v[240:243], 0
	ds_read_b128 v[20:23], v133 offset:32
	s_waitcnt lgkmcnt(0)
	v_mfma_f32_32x32x16_bf16 v[32:47], v[20:23], v[244:247], v[32:47]
	ds_read_b128 v[20:23], v133 offset:64
	s_waitcnt lgkmcnt(0)
	v_mfma_f32_32x32x16_bf16 v[32:47], v[20:23], v[248:251], v[32:47]
	ds_read_b128 v[20:23], v133 offset:96
	s_waitcnt vmcnt(15)
	ds_write_b128 v175, v[48:51]
	s_waitcnt vmcnt(14)
	ds_write_b128 v128, v[52:55]
	s_waitcnt vmcnt(13)
	ds_write_b128 v129, v[56:59]
	s_waitcnt vmcnt(12)
	ds_write_b128 v130, v[60:63]
	s_waitcnt lgkmcnt(4)
	v_mfma_f32_32x32x16_bf16 v[32:47], v[20:23], v[252:255], v[32:47]
	ds_read_b128 v[20:23], v131
	s_waitcnt lgkmcnt(0)
	v_mfma_f32_32x32x16_bf16 v[64:79], v[20:23], v[240:243], 0
	ds_read_b128 v[20:23], v131 offset:32
	s_waitcnt lgkmcnt(0)
	v_mfma_f32_32x32x16_bf16 v[64:79], v[20:23], v[244:247], v[64:79]
	ds_read_b128 v[20:23], v131 offset:64
	s_waitcnt lgkmcnt(0)
	v_mfma_f32_32x32x16_bf16 v[64:79], v[20:23], v[248:251], v[64:79]
	ds_read_b128 v[20:23], v131 offset:96
	s_waitcnt vmcnt(5)
	ds_write_b128 v132, v[116:119]
	ds_write_b128 v134, v[92:95]
	ds_write_b128 v135, v[96:99]
	ds_write_b128 v136, v[100:103]
	s_waitcnt lgkmcnt(4)
	v_mfma_f32_32x32x16_bf16 v[64:79], v[20:23], v[252:255], v[64:79]
	ds_read_b128 v[20:23], v133
	s_waitcnt lgkmcnt(0)
	v_mfma_f32_32x32x16_bf16 v[48:63], v[20:23], v[240:243], 0
	ds_read_b128 v[20:23], v133 offset:32
	s_waitcnt lgkmcnt(0)
	v_mfma_f32_32x32x16_bf16 v[48:63], v[20:23], v[244:247], v[48:63]
	ds_read_b128 v[20:23], v133 offset:64
	s_waitcnt lgkmcnt(0)
	v_mfma_f32_32x32x16_bf16 v[48:63], v[20:23], v[248:251], v[48:63]
	ds_read_b128 v[20:23], v133 offset:96
	ds_write_b128 v175, v[104:107]
	ds_write_b128 v128, v[108:111]
	ds_write_b128 v129, v[112:115]
	s_waitcnt vmcnt(4)
	ds_write_b128 v130, v[120:123]
	ds_read_b128 v[92:95], v131 offset:32
	s_waitcnt lgkmcnt(5)
	v_mfma_f32_32x32x16_bf16 v[48:63], v[20:23], v[252:255], v[48:63]
	ds_read_b128 v[20:23], v131
	s_waitcnt lgkmcnt(0)
	v_mfma_f32_32x32x16_bf16 v[16:31], v[20:23], v[240:243], 0
	v_mfma_f32_32x32x16_bf16 v[16:31], v[92:95], v[244:247], v[16:31]
	ds_read_b128 v[88:91], v131 offset:64
	s_waitcnt lgkmcnt(0)
	v_mfma_f32_32x32x16_bf16 v[16:31], v[88:91], v[248:251], v[16:31]
	ds_read_b128 v[84:87], v131 offset:96
	s_waitcnt lgkmcnt(0)
	v_mfma_f32_32x32x16_bf16 v[16:31], v[84:87], v[252:255], v[16:31]
	global_load_dwordx4 v[140:143], v124, s[42:43]
	global_load_dwordx4 v[136:139], v125, s[42:43]
	global_load_dwordx4 v[132:135], v126, s[42:43]
	global_load_dwordx4 v[128:131], v127, s[42:43]
	global_load_dwordx4 v[112:115], v155, s[42:43]
	global_load_dwordx4 v[116:119], v157, s[42:43]
	global_load_dwordx4 v[120:123], v159, s[42:43]
	s_nop 0
	global_load_dwordx4 v[124:127], v161, s[42:43]
	global_load_dwordx4 v[96:99], v163, s[42:43]
	global_load_dwordx4 v[100:103], v165, s[42:43]
	global_load_dwordx4 v[104:107], v167, s[42:43]
	global_load_dwordx4 v[108:111], v186, s[42:43]
	v_add_u32_e32 v80, 0x100, v187
	v_cmp_gt_i32_e32 vcc, s0, v80
	v_lshlrev_b32_e32 v80, 4, v80
	s_waitcnt vmcnt(15)
	global_store_dwordx4 v190, v[146:149], s[18:19] nt
	s_waitcnt vmcnt(15)
	global_store_dwordx4 v191, v[150:153], s[18:19] nt
	s_waitcnt vmcnt(15)
	global_store_dwordx4 v192, v[178:181], s[18:19] nt
	s_waitcnt vmcnt(15)
	global_store_dwordx4 v193, v[182:185], s[18:19] nt
	v_cndmask_b32_e32 v81, v188, v189, vcc
	v_lshl_add_u32 v146, v81, 14, v80
	v_add_u32_e32 v80, 0x140, v187
	v_cmp_gt_i32_e32 vcc, s0, v80
	v_add_u32_e32 v88, 0x180, v187
	v_lshlrev_b32_e32 v80, 4, v80
	v_cndmask_b32_e32 v81, v188, v189, vcc
	v_cmp_gt_i32_e32 vcc, s0, v88
	v_lshlrev_b32_e32 v88, 4, v88
	v_lshl_add_u32 v148, v81, 14, v80
	v_cndmask_b32_e32 v89, v188, v189, vcc
	v_lshl_add_u32 v150, v89, 14, v88
	v_add_u32_e32 v88, 0x1c0, v187
	v_cmp_gt_i32_e32 vcc, s0, v88
	v_lshlrev_b32_e32 v88, 4, v88
	global_load_dwordx4 v[84:87], v146, s[36:37] nt
	global_load_dwordx4 v[80:83], v148, s[36:37] nt
	v_cndmask_b32_e32 v89, v188, v189, vcc
	v_lshl_add_u32 v152, v89, 14, v88
	global_load_dwordx4 v[92:95], v150, s[36:37] nt
	global_load_dwordx4 v[88:91], v152, s[36:37] nt
	s_add_i32 s13, s86, 1
	s_cmp_lg_u32 s56, 0
	s_cselect_b32 s12, s86, s13
	s_cselect_b32 s14, 1, 0
	s_min_i32 s12, s12, 2
	s_lshl_b32 s13, s12, 1
	s_or_b32 s14, s14, s73
	s_lshl_b32 s15, -1, s13
	s_andn2_b32 s15, s14, s15
	s_or_b32 s15, s15, s84
	s_lshr_b32 s14, s14, s13
	s_add_i32 s17, s13, 5
	s_lshl_b32 s14, s14, s17
	s_add_i32 s15, s15, s14
	s_add_i32 s15, s15, s34
	v_lshlrev_b32_e32 v194, s13, v176
	v_add_u32_e32 v194, s15, v194
	v_mul_lo_u32 v194, v194, s75
	v_lshlrev_b32_e32 v195, 4, v173
	v_add3_u32 v194, v195, s10, v194
	global_load_dwordx4 v[240:243], v194, s[28:29]
	global_load_dwordx4 v[244:247], v194, s[28:29] offset:32
	global_load_dwordx4 v[248:251], v194, s[28:29] offset:64
	global_load_dwordx4 v[252:255], v194, s[28:29] offset:96
	s_ashr_i32 s0, s1, s87
	s_sub_i32 s1, 0x80, s0
	v_max_i32_e32 v147, s1, v176
	v_sub_u32_e32 v147, v147, v177
	v_cmp_gt_i32_e32 vcc, 1, v147
	s_sub_i32 s1, 0x7f, s0
	s_ashr_i32 s1, s1, 5
	v_cndmask_b32_e32 v192, v171, v0, vcc
	v_cmp_gt_i32_e32 vcc, 2, v147
	s_cmpk_lt_i32 s0, 0x80
	s_cselect_b32 s0, s1, -1
	v_cndmask_b32_e32 v190, v171, v1, vcc
	v_cmp_gt_i32_e32 vcc, 3, v147
	s_mov_b32 s1, 0xff800000
	v_max3_f32 v0, v192, s1, v190
	v_cndmask_b32_e32 v193, v171, v2, vcc
	v_cmp_gt_i32_e32 vcc, 4, v147
	s_cmp_lt_i32 s0, 1
	s_mov_b64 s[36:37], -1
	v_cndmask_b32_e32 v191, v171, v3, vcc
	v_cmp_gt_i32_e32 vcc, 9, v147
	v_max3_f32 v0, v0, v193, v191
	s_nop 0
	v_cndmask_b32_e32 v189, v171, v4, vcc
	v_cmp_gt_i32_e32 vcc, 10, v147
	s_nop 1
	v_cndmask_b32_e32 v187, v171, v5, vcc
	v_cmp_gt_i32_e32 vcc, 11, v147
	v_max3_f32 v0, v0, v189, v187
	s_nop 0
	v_cndmask_b32_e32 v188, v171, v6, vcc
	v_cmp_gt_i32_e32 vcc, 12, v147
	s_nop 1
	v_cndmask_b32_e32 v186, v171, v7, vcc
	v_cmp_gt_i32_e32 vcc, 17, v147
	v_max3_f32 v0, v0, v188, v186
	s_nop 0
	v_cndmask_b32_e32 v185, v171, v8, vcc
	v_cmp_gt_i32_e32 vcc, 18, v147
	s_nop 1
	v_cndmask_b32_e32 v183, v171, v9, vcc
	v_cmp_gt_i32_e32 vcc, 19, v147
	v_max3_f32 v0, v0, v185, v183
	s_nop 0
	v_cndmask_b32_e32 v184, v171, v10, vcc
	v_cmp_gt_i32_e32 vcc, 20, v147
	s_nop 1
	v_cndmask_b32_e32 v182, v171, v11, vcc
	v_cmp_gt_i32_e32 vcc, 25, v147
	v_max3_f32 v0, v0, v184, v182
	s_nop 0
	v_cndmask_b32_e32 v181, v171, v12, vcc
	v_cmp_gt_i32_e32 vcc, 26, v147
	s_nop 1
	v_cndmask_b32_e32 v179, v171, v13, vcc
	v_cmp_gt_i32_e32 vcc, 27, v147
	v_max3_f32 v0, v0, v181, v179
	s_nop 0
	v_cndmask_b32_e32 v180, v171, v14, vcc
	v_cmp_gt_i32_e32 vcc, 28, v147
	s_nop 1
	v_cndmask_b32_e32 v178, v171, v15, vcc
	v_max3_f32 v149, v0, v180, v178
	s_cbranch_scc1 .LBB0_346
	v_cmp_gt_i32_e32 vcc, 33, v147
	s_nop 1
	v_cndmask_b32_e32 v0, v171, v32, vcc
	v_cmp_gt_i32_e32 vcc, 34, v147
	s_nop 1
	v_cndmask_b32_e32 v1, v171, v33, vcc
	v_cmp_gt_i32_e32 vcc, 35, v147
	v_max3_f32 v4, v149, v0, v1
	s_nop 0
	v_cndmask_b32_e32 v2, v171, v34, vcc
	v_cmp_gt_i32_e32 vcc, 36, v147
	s_nop 1
	v_cndmask_b32_e32 v3, v171, v35, vcc
	v_cmp_gt_i32_e32 vcc, 41, v147
	v_max3_f32 v6, v4, v2, v3
	s_nop 0
	v_cndmask_b32_e32 v4, v171, v36, vcc
	v_cmp_gt_i32_e32 vcc, 42, v147
	s_nop 1
	v_cndmask_b32_e32 v5, v171, v37, vcc
	v_cmp_gt_i32_e32 vcc, 43, v147
	v_max3_f32 v8, v6, v4, v5
	s_nop 0
	v_cndmask_b32_e32 v6, v171, v38, vcc
	v_cmp_gt_i32_e32 vcc, 44, v147
	s_nop 1
	v_cndmask_b32_e32 v7, v171, v39, vcc
	v_cmp_gt_i32_e32 vcc, 49, v147
	v_max3_f32 v10, v8, v6, v7
	s_nop 0
	v_cndmask_b32_e32 v8, v171, v40, vcc
	v_cmp_gt_i32_e32 vcc, 50, v147
	s_nop 1
	v_cndmask_b32_e32 v9, v171, v41, vcc
	v_cmp_gt_i32_e32 vcc, 51, v147
	v_max3_f32 v12, v10, v8, v9
	s_nop 0
	v_cndmask_b32_e32 v10, v171, v42, vcc
	v_cmp_gt_i32_e32 vcc, 52, v147
	s_nop 1
	v_cndmask_b32_e32 v11, v171, v43, vcc
	v_cmp_gt_i32_e32 vcc, 57, v147
	v_max3_f32 v14, v12, v10, v11
	s_nop 0
	v_cndmask_b32_e32 v12, v171, v44, vcc
	v_cmp_gt_i32_e32 vcc, 58, v147
	s_nop 1
	v_cndmask_b32_e32 v13, v171, v45, vcc
	v_cmp_gt_i32_e32 vcc, 59, v147
	v_max3_f32 v151, v14, v12, v13
	s_nop 0
	v_cndmask_b32_e32 v14, v171, v46, vcc
	v_cmp_gt_i32_e32 vcc, 60, v147
	s_nop 1
	v_cndmask_b32_e32 v15, v171, v47, vcc
	v_max3_f32 v151, v151, v14, v15
	s_cbranch_execnz .LBB0_348
	s_branch .LBB0_347
